# in-proj GEMM: first K-iteration of every non-first unit peeled: accumulators start from C=0 in the first-touch MFMAs (no 128 v_mov) and the first two phase waits are vmcnt(24) so the MFMAs overlap the
# speedup vs baseline: 1.0021x; 1.0021x over previous
; #define PG8_STAGE(bufoff, gbase, voff) do { _Pragma("unroll") for (int _i = 0; _i < 2; ++_i) \
;         __builtin_amdgcn_global_load_lds((const unsigned*)((const char*)(gbase) + (voff)[_i]), (LAS unsigned*)(lds + (bufoff) + ldsw + _i * 8192), 16, 0, 0); } while (0)
; #define PG8_LDA(dst, b, h) do { _Pragma("unroll") for (int m = 0; m < 4; ++m) _Pragma("unroll") for (int k = 0; k < 2; ++k) dst[m][k] = *(const LAS bf16x8*)(lds + PG8_SA(b, h) + aoff + m * 2048 + k * 1024); } while (0)
; #define PG8_LDB(dst, b, h) do { _Pragma("unroll") for (int n = 0; n < 2; ++n) _Pragma("unroll") for (int k = 0; k < 2; ++k) dst[n][k] = *(const LAS bf16x8*)(lds + PG8_SB(b, h) + boff + n * 2048 + k * 1024); } while (0)
; #define PG8_MMA(ai, bj, At, Bt) do { __builtin_amdgcn_s_setprio(1); _Pragma("unroll") for (int m = 0; m < 4; ++m) _Pragma("unroll") for (int n = 0; n < 2; ++n) _Pragma("unroll") for (int k = 0; k < 2; ++k) \
;         acc[ai][bj][m][n] = __builtin_amdgcn_mfma_f32_16x16x32_bf16(Bt[n][k], At[m][k], acc[ai][bj][m][n], 0, 0, 0); __builtin_amdgcn_s_setprio(0); } while (0)
; #define PG8_BAR __builtin_amdgcn_s_barrier()
; template <class Epi, class Sched>
; __device__ __forceinline__ void gemm_phase(LAS unsigned char* lds, const Gemm g, const Sched& S, const Epi& E, const int wid) {
;     ...
;         for (int t = 0; t < nt; t += 2) {
;             const bool last = (t == nt - 2);
;             const char* a1 = cA + (size_t)(t + 1) * kstep;
;             const char* a2 = last ? nA : cA + (size_t)(t + 2) * kstep; const char* b2 = last ? nB : cB + (size_t)(t + 2) * kstep;
;             const char* a3 = a2 + kstep; const char* b3 = b2 + kstep;
;             if constexpr (Epi::MID) { if (t == nt / 2) E.mid(acc, cur, ui, wr, wc, fr, fq); }
;             PG8_LDB(B0, 0, 0); PG8_LDB(B1, 0, 1); PG8_SCHED; PG8_LDA(At, 0, 0); PG8_STAGE(PG8_SA(1, 1), a1 + hstep, voffA);
;             PG8_WAIT_V(8); PG8_WAIT_L(0); PG8_BAR; PG8_MMA(0, 0, At, B0); PG8_MMA(0, 1, At, B1); PG8_BAR; PG8_SCHED;
;     ...
;         if constexpr (Epi::INIT) E.init(acc, nxt, ui + 1, wr, wc, fr, fq);
;         else {
; #pragma unroll
;         for (int a = 0; a < 2; ++a)
; #pragma unroll
;             for (int b = 0; b < 2; ++b)
; #pragma unroll
;                 for (int m = 0; m < 4; ++m)
; #pragma unroll
;                     for (int n = 0; n < 2; ++n) acc[a][b][m][n] = (f32x4){0.f, 0.f, 0.f, 0.f};
;         }
.LBB0_75:
	s_ashr_i32 s17, s16, 31
	s_lshl_b64 s[10:11], s[16:17], 20
	s_add_u32 s10, s54, s10
	s_addc_u32 s11, s55, s11
	s_and_b64 s[12:13], s[42:43], exec
	s_cselect_b32 s17, s11, s19
	s_cselect_b32 s24, s10, s18
	s_ashr_i32 s15, s14, 31
	s_lshl_b64 s[12:13], s[14:15], 20
	s_add_u32 s12, s38, s12
	s_addc_u32 s13, s39, s13
	s_and_b64 s[22:23], s[42:43], exec
	s_cselect_b32 s15, s13, s21
	s_cselect_b32 s25, s12, s20
	s_add_u32 s18, s18, 0x80080
	s_addc_u32 s19, s19, 0
	s_add_u32 s44, s20, 0x100
	s_addc_u32 s78, s21, 0
	s_mov_b32 s79, -2
	s_cmp_eq_u32 s9, 0
	s_cbranch_scc0 .Lmy_p1_peel
	v_mov_b32_e32 v2, 0
	v_mov_b32_e32 v3, v2
	v_mov_b32_e32 v4, v2
	v_mov_b32_e32 v5, v2
	v_mov_b32_e32 v6, v2
	v_mov_b32_e32 v7, v2
	v_mov_b32_e32 v8, v2
	v_mov_b32_e32 v9, v2
	v_mov_b32_e32 v18, v2
	v_mov_b32_e32 v19, v2
	v_mov_b32_e32 v20, v2
	v_mov_b32_e32 v21, v2
	v_mov_b32_e32 v22, v2
	v_mov_b32_e32 v23, v2
	v_mov_b32_e32 v24, v2
	v_mov_b32_e32 v25, v2
	v_mov_b32_e32 v34, v2
	v_mov_b32_e32 v35, v2
	v_mov_b32_e32 v36, v2
	v_mov_b32_e32 v37, v2
	v_mov_b32_e32 v38, v2
	v_mov_b32_e32 v39, v2
	v_mov_b32_e32 v40, v2
	v_mov_b32_e32 v41, v2
	v_mov_b32_e32 v50, v2
	v_mov_b32_e32 v51, v2
	v_mov_b32_e32 v52, v2
	v_mov_b32_e32 v53, v2
	v_mov_b32_e32 v54, v2
	v_mov_b32_e32 v55, v2
	v_mov_b32_e32 v56, v2
	v_mov_b32_e32 v57, v2
	v_mov_b32_e32 v10, v2
	v_mov_b32_e32 v11, v2
	v_mov_b32_e32 v12, v2
	v_mov_b32_e32 v13, v2
	v_mov_b32_e32 v14, v2
	v_mov_b32_e32 v15, v2
	v_mov_b32_e32 v16, v2
	v_mov_b32_e32 v17, v2
	v_mov_b32_e32 v26, v2
	v_mov_b32_e32 v27, v2
	v_mov_b32_e32 v28, v2
	v_mov_b32_e32 v29, v2
	v_mov_b32_e32 v30, v2
	v_mov_b32_e32 v31, v2
	v_mov_b32_e32 v32, v2
	v_mov_b32_e32 v33, v2
	v_mov_b32_e32 v42, v2
	v_mov_b32_e32 v43, v2
	v_mov_b32_e32 v44, v2
	v_mov_b32_e32 v45, v2
	v_mov_b32_e32 v46, v2
	v_mov_b32_e32 v47, v2
	v_mov_b32_e32 v48, v2
	v_mov_b32_e32 v49, v2
	v_mov_b32_e32 v58, v2
	v_mov_b32_e32 v59, v2
	v_mov_b32_e32 v60, v2
	v_mov_b32_e32 v61, v2
	v_mov_b32_e32 v62, v2
	v_mov_b32_e32 v63, v2
	v_mov_b32_e32 v64, v2
	v_mov_b32_e32 v65, v2
	v_mov_b32_e32 v66, v2
	v_mov_b32_e32 v67, v2
	v_mov_b32_e32 v68, v2
	v_mov_b32_e32 v69, v2
	v_mov_b32_e32 v70, v2
	v_mov_b32_e32 v71, v2
	v_mov_b32_e32 v72, v2
	v_mov_b32_e32 v73, v2
	v_mov_b32_e32 v82, v2
	v_mov_b32_e32 v83, v2
	v_mov_b32_e32 v84, v2
	v_mov_b32_e32 v85, v2
	v_mov_b32_e32 v86, v2
	v_mov_b32_e32 v87, v2
	v_mov_b32_e32 v88, v2
	v_mov_b32_e32 v89, v2
	v_mov_b32_e32 v98, v2
	v_mov_b32_e32 v99, v2
	v_mov_b32_e32 v100, v2
	v_mov_b32_e32 v101, v2
	v_mov_b32_e32 v102, v2
	v_mov_b32_e32 v103, v2
	v_mov_b32_e32 v104, v2
	v_mov_b32_e32 v105, v2
	v_mov_b32_e32 v114, v2
	v_mov_b32_e32 v115, v2
	v_mov_b32_e32 v116, v2
	v_mov_b32_e32 v117, v2
	v_mov_b32_e32 v118, v2
	v_mov_b32_e32 v119, v2
	v_mov_b32_e32 v120, v2
	v_mov_b32_e32 v121, v2
	v_mov_b32_e32 v74, v2
	v_mov_b32_e32 v75, v2
	v_mov_b32_e32 v76, v2
	v_mov_b32_e32 v77, v2
	v_mov_b32_e32 v78, v2
	v_mov_b32_e32 v79, v2
	v_mov_b32_e32 v80, v2
	v_mov_b32_e32 v81, v2
	v_mov_b32_e32 v90, v2
	v_mov_b32_e32 v91, v2
	v_mov_b32_e32 v92, v2
	v_mov_b32_e32 v93, v2
	v_mov_b32_e32 v94, v2
	v_mov_b32_e32 v95, v2
	v_mov_b32_e32 v96, v2
	v_mov_b32_e32 v97, v2
	v_mov_b32_e32 v106, v2
	v_mov_b32_e32 v107, v2
	v_mov_b32_e32 v108, v2
	v_mov_b32_e32 v109, v2
	v_mov_b32_e32 v110, v2
	v_mov_b32_e32 v111, v2
	v_mov_b32_e32 v112, v2
	v_mov_b32_e32 v113, v2
	v_mov_b32_e32 v122, v2
	v_mov_b32_e32 v123, v2
	v_mov_b32_e32 v124, v2
	v_mov_b32_e32 v125, v2
	v_mov_b32_e32 v126, v2
	v_mov_b32_e32 v127, v2
	v_mov_b32_e32 v128, v2
	v_mov_b32_e32 v129, v2
	s_branch .LBB0_76
.Lmy_p1_peel:
	s_add_u32 s20, s18, 0xfff80080
	s_addc_u32 s21, s19, -1
	s_add_i32 s80, 0, 0x10000
	s_cmp_eq_u32 s79, 28
	s_cselect_b32 s23, s17, s21
	s_cselect_b32 s22, s24, s20
	v_add_u32_e32 v0, s80, v160
	s_cselect_b32 s21, s15, s78
	s_cselect_b32 s20, s25, s44
	s_add_i32 s81, 0, 0x14000
	ds_read_b128 v[130:133], v0
	s_waitcnt lgkmcnt(0)
	ds_read_b128 v[134:137], v0 offset:1024
	ds_read_b128 v[156:159], v0 offset:2048
	ds_read_b128 v[192:195], v0 offset:3072
	v_add_u32_e32 v0, s81, v160
	ds_read_b128 v[196:199], v0
	ds_read_b128 v[200:203], v0 offset:1024
	ds_read_b128 v[204:207], v0 offset:2048
	ds_read_b128 v[208:211], v0 offset:3072
	v_lshl_add_u64 v[244:245], s[18:19], 0, v[152:153]
	s_add_i32 m0, s47, 0xc000
	ds_read_b128 v[212:215], v183
	ds_read_b128 v[216:219], v183 offset:1024
	ds_read_b128 v[220:223], v183 offset:2048
	ds_read_b128 v[224:227], v183 offset:3072
	ds_read_b128 v[228:231], v183 offset:4096
	ds_read_b128 v[232:235], v183 offset:5120
	ds_read_b128 v[236:239], v183 offset:6144
	ds_read_b128 v[240:243], v183 offset:7168
	global_load_lds_dwordx4 v[244:245], off
	v_lshl_add_u64 v[244:245], s[18:19], 0, v[154:155]
	s_add_i32 m0, s47, 0xe000
	s_nop 0
	global_load_lds_dwordx4 v[244:245], off
	s_waitcnt vmcnt(24)
	s_waitcnt lgkmcnt(0)
	s_barrier
; #define PG8_STAGE(bufoff, gbase, voff) do { _Pragma("unroll") for (int _i = 0; _i < 2; ++_i) \
;         __builtin_amdgcn_global_load_lds((const unsigned*)((const char*)(gbase) + (voff)[_i]), (LAS unsigned*)(lds + (bufoff) + ldsw + _i * 8192), 16, 0, 0); } while (0)
; #define PG8_LDA(dst, b, h) do { _Pragma("unroll") for (int m = 0; m < 4; ++m) _Pragma("unroll") for (int k = 0; k < 2; ++k) dst[m][k] = *(const LAS bf16x8*)(lds + PG8_SA(b, h) + aoff + m * 2048 + k * 1024); } while (0)
; #define PG8_LDB(dst, b, h) do { _Pragma("unroll") for (int n = 0; n < 2; ++n) _Pragma("unroll") for (int k = 0; k < 2; ++k) dst[n][k] = *(const LAS bf16x8*)(lds + PG8_SB(b, h) + boff + n * 2048 + k * 1024); } while (0)
; #define PG8_MMA(ai, bj, At, Bt) do { __builtin_amdgcn_s_setprio(1); _Pragma("unroll") for (int m = 0; m < 4; ++m) _Pragma("unroll") for (int n = 0; n < 2; ++n) _Pragma("unroll") for (int k = 0; k < 2; ++k) \
;         acc[ai][bj][m][n] = __builtin_amdgcn_mfma_f32_16x16x32_bf16(Bt[n][k], At[m][k], acc[ai][bj][m][n], 0, 0, 0); __builtin_amdgcn_s_setprio(0); } while (0)
; #define PG8_WAIT_V(n) asm volatile("s_waitcnt vmcnt(" #n ")" ::: "memory")
; #define PG8_WAIT_L(n) asm volatile("s_waitcnt lgkmcnt(" #n ")" ::: "memory")
; #define PG8_BAR __builtin_amdgcn_s_barrier()
; #define PG8_SCHED __builtin_amdgcn_sched_barrier(0)
; template <class Epi, class Sched>
; __device__ __forceinline__ void gemm_phase(LAS unsigned char* lds, const Gemm g, const Sched& S, const Epi& E, const int wid) {
;     ...
;             PG8_LDB(B0, 0, 0); PG8_LDB(B1, 0, 1); PG8_SCHED; PG8_LDA(At, 0, 0); PG8_STAGE(PG8_SA(1, 1), a1 + hstep, voffA);
;             PG8_WAIT_V(8); PG8_WAIT_L(0); PG8_BAR; PG8_MMA(0, 0, At, B0); PG8_MMA(0, 1, At, B1); PG8_BAR; PG8_SCHED;
;             PG8_LDA(At, 0, 1); PG8_STAGE(PG8_SB(0, 0), b2, voffB); PG8_STAGE(PG8_SB(0, 1), b2 + bstep, voffB); PG8_STAGE(PG8_SA(0, 0), a2, voffA);
;             PG8_WAIT_V(8); PG8_WAIT_L(0); PG8_BAR; PG8_MMA(1, 0, At, B0); PG8_MMA(1, 1, At, B1); PG8_BAR; PG8_SCHED;
	s_setprio 1
	s_waitcnt lgkmcnt(0)
	v_mfma_f32_16x16x32_bf16 v[126:129], v[130:133], v[212:215], 0
	v_mfma_f32_16x16x32_bf16 v[122:125], v[156:159], v[212:215], 0
	v_mfma_f32_16x16x32_bf16 v[110:113], v[130:133], v[220:223], 0
	v_mfma_f32_16x16x32_bf16 v[106:109], v[156:159], v[220:223], 0
	v_mfma_f32_16x16x32_bf16 v[94:97], v[130:133], v[228:231], 0
	v_mfma_f32_16x16x32_bf16 v[90:93], v[156:159], v[228:231], 0
	v_mfma_f32_16x16x32_bf16 v[78:81], v[130:133], v[236:239], 0
	v_mfma_f32_16x16x32_bf16 v[74:77], v[156:159], v[236:239], 0
	v_mfma_f32_16x16x32_bf16 v[126:129], v[134:137], v[216:219], v[126:129]
	v_mfma_f32_16x16x32_bf16 v[122:125], v[192:195], v[216:219], v[122:125]
	v_mfma_f32_16x16x32_bf16 v[110:113], v[134:137], v[224:227], v[110:113]
	v_mfma_f32_16x16x32_bf16 v[106:109], v[192:195], v[224:227], v[106:109]
	v_mfma_f32_16x16x32_bf16 v[94:97], v[134:137], v[232:235], v[94:97]
	v_mfma_f32_16x16x32_bf16 v[90:93], v[192:195], v[232:235], v[90:93]
	v_mfma_f32_16x16x32_bf16 v[78:81], v[134:137], v[240:243], v[78:81]
	v_mfma_f32_16x16x32_bf16 v[74:77], v[192:195], v[240:243], v[74:77]
	s_setprio 0
	s_setprio 1
	v_mfma_f32_16x16x32_bf16 v[118:121], v[196:199], v[212:215], 0
	v_mfma_f32_16x16x32_bf16 v[114:117], v[204:207], v[212:215], 0
	v_mfma_f32_16x16x32_bf16 v[102:105], v[196:199], v[220:223], 0
	v_mfma_f32_16x16x32_bf16 v[98:101], v[204:207], v[220:223], 0
	v_mfma_f32_16x16x32_bf16 v[86:89], v[196:199], v[228:231], 0
	v_mfma_f32_16x16x32_bf16 v[82:85], v[204:207], v[228:231], 0
	v_mfma_f32_16x16x32_bf16 v[70:73], v[196:199], v[236:239], 0
	v_mfma_f32_16x16x32_bf16 v[66:69], v[204:207], v[236:239], 0
	v_mfma_f32_16x16x32_bf16 v[118:121], v[200:203], v[216:219], v[118:121]
	v_mfma_f32_16x16x32_bf16 v[114:117], v[208:211], v[216:219], v[114:117]
	v_mfma_f32_16x16x32_bf16 v[102:105], v[200:203], v[224:227], v[102:105]
	v_mfma_f32_16x16x32_bf16 v[98:101], v[208:211], v[224:227], v[98:101]
	v_mfma_f32_16x16x32_bf16 v[86:89], v[200:203], v[232:235], v[86:89]
	v_mfma_f32_16x16x32_bf16 v[82:85], v[208:211], v[232:235], v[82:85]
	v_mfma_f32_16x16x32_bf16 v[70:73], v[200:203], v[240:243], v[70:73]
	v_mfma_f32_16x16x32_bf16 v[66:69], v[208:211], v[240:243], v[66:69]
	s_setprio 0
	s_barrier
	s_add_i32 s80, s80, s97
	v_lshl_add_u64 v[244:245], s[20:21], 0, v[140:141]
	s_mov_b32 m0, s80
	ds_read_b128 v[212:215], v183 offset:16384
	ds_read_b128 v[216:219], v183 offset:17408
	ds_read_b128 v[220:223], v183 offset:18432
	ds_read_b128 v[224:227], v183 offset:19456
	ds_read_b128 v[228:231], v183 offset:20480
	ds_read_b128 v[232:235], v183 offset:21504
	ds_read_b128 v[236:239], v183 offset:22528
	ds_read_b128 v[240:243], v183 offset:23552
	global_load_lds_dwordx4 v[244:245], off
	s_add_i32 m0, s80, 0x2000
	s_add_u32 vcc_lo, s20, 0x20000
	v_lshl_add_u64 v[246:247], s[20:21], 0, v[144:145]
	s_addc_u32 vcc_hi, s21, 0
	s_add_i32 s80, s81, s97
	global_load_lds_dwordx4 v[246:247], off
	v_lshl_add_u64 v[248:249], vcc, 0, v[140:141]
	s_mov_b32 m0, s80
	v_lshl_add_u64 v[162:163], s[22:23], 0, v[142:143]
	global_load_lds_dwordx4 v[248:249], off
	v_lshl_add_u64 v[248:249], vcc, 0, v[144:145]
	s_add_i32 m0, s80, 0x2000
	s_nop 0
	global_load_lds_dwordx4 v[248:249], off
	v_lshl_add_u64 v[248:249], s[22:23], 0, v[138:139]
	s_mov_b32 m0, s47
	s_nop 0
	global_load_lds_dwordx4 v[248:249], off
	s_mov_b32 m0, s91
	s_nop 0
	global_load_lds_dwordx4 v[162:163], off
	s_waitcnt vmcnt(24)
	s_waitcnt lgkmcnt(0)
	s_barrier
	s_setprio 1
	s_waitcnt lgkmcnt(0)
	v_mfma_f32_16x16x32_bf16 v[62:65], v[130:133], v[212:215], 0
	v_mfma_f32_16x16x32_bf16 v[58:61], v[156:159], v[212:215], 0
	v_mfma_f32_16x16x32_bf16 v[46:49], v[130:133], v[220:223], 0
	v_mfma_f32_16x16x32_bf16 v[42:45], v[156:159], v[220:223], 0
	v_mfma_f32_16x16x32_bf16 v[30:33], v[130:133], v[228:231], 0
	v_mfma_f32_16x16x32_bf16 v[26:29], v[156:159], v[228:231], 0
	v_mfma_f32_16x16x32_bf16 v[14:17], v[130:133], v[236:239], 0
	v_mfma_f32_16x16x32_bf16 v[10:13], v[156:159], v[236:239], 0
	v_mfma_f32_16x16x32_bf16 v[62:65], v[134:137], v[216:219], v[62:65]
	v_mfma_f32_16x16x32_bf16 v[58:61], v[192:195], v[216:219], v[58:61]
	v_mfma_f32_16x16x32_bf16 v[46:49], v[134:137], v[224:227], v[46:49]
	v_mfma_f32_16x16x32_bf16 v[42:45], v[192:195], v[224:227], v[42:45]
	v_mfma_f32_16x16x32_bf16 v[30:33], v[134:137], v[232:235], v[30:33]
	v_mfma_f32_16x16x32_bf16 v[26:29], v[192:195], v[232:235], v[26:29]
	v_mfma_f32_16x16x32_bf16 v[14:17], v[134:137], v[240:243], v[14:17]
	v_mfma_f32_16x16x32_bf16 v[10:13], v[192:195], v[240:243], v[10:13]
	s_setprio 0
	s_setprio 1
	v_mfma_f32_16x16x32_bf16 v[54:57], v[196:199], v[212:215], 0
	v_mfma_f32_16x16x32_bf16 v[50:53], v[204:207], v[212:215], 0
	v_mfma_f32_16x16x32_bf16 v[38:41], v[196:199], v[220:223], 0
	v_mfma_f32_16x16x32_bf16 v[34:37], v[204:207], v[220:223], 0
	v_mfma_f32_16x16x32_bf16 v[22:25], v[196:199], v[228:231], 0
	v_mfma_f32_16x16x32_bf16 v[18:21], v[204:207], v[228:231], 0
	v_mfma_f32_16x16x32_bf16 v[6:9], v[196:199], v[236:239], 0
	v_mfma_f32_16x16x32_bf16 v[2:5], v[204:207], v[236:239], 0
	v_mfma_f32_16x16x32_bf16 v[54:57], v[200:203], v[216:219], v[54:57]
	v_mfma_f32_16x16x32_bf16 v[50:53], v[208:211], v[216:219], v[50:53]
	v_mfma_f32_16x16x32_bf16 v[38:41], v[200:203], v[224:227], v[38:41]
	v_mfma_f32_16x16x32_bf16 v[34:37], v[208:211], v[224:227], v[34:37]
	v_mfma_f32_16x16x32_bf16 v[22:25], v[200:203], v[232:235], v[22:25]
	v_mfma_f32_16x16x32_bf16 v[18:21], v[208:211], v[232:235], v[18:21]
	v_mfma_f32_16x16x32_bf16 v[6:9], v[200:203], v[240:243], v[6:9]
	v_mfma_f32_16x16x32_bf16 v[2:5], v[208:211], v[240:243], v[2:5]
	s_setprio 0
	s_barrier
; #define PG8_STAGE(bufoff, gbase, voff) do { _Pragma("unroll") for (int _i = 0; _i < 2; ++_i) \
;         __builtin_amdgcn_global_load_lds((const unsigned*)((const char*)(gbase) + (voff)[_i]), (LAS unsigned*)(lds + (bufoff) + ldsw + _i * 8192), 16, 0, 0); } while (0)
; #define PG8_LDA(dst, b, h) do { _Pragma("unroll") for (int m = 0; m < 4; ++m) _Pragma("unroll") for (int k = 0; k < 2; ++k) dst[m][k] = *(const LAS bf16x8*)(lds + PG8_SA(b, h) + aoff + m * 2048 + k * 1024); } while (0)
; #define PG8_LDB(dst, b, h) do { _Pragma("unroll") for (int n = 0; n < 2; ++n) _Pragma("unroll") for (int k = 0; k < 2; ++k) dst[n][k] = *(const LAS bf16x8*)(lds + PG8_SB(b, h) + boff + n * 2048 + k * 1024); } while (0)
; #define PG8_MMA(ai, bj, At, Bt) do { __builtin_amdgcn_s_setprio(1); _Pragma("unroll") for (int m = 0; m < 4; ++m) _Pragma("unroll") for (int n = 0; n < 2; ++n) _Pragma("unroll") for (int k = 0; k < 2; ++k) \
;         acc[ai][bj][m][n] = __builtin_amdgcn_mfma_f32_16x16x32_bf16(Bt[n][k], At[m][k], acc[ai][bj][m][n], 0, 0, 0); __builtin_amdgcn_s_setprio(0); } while (0)
; #define PG8_WAIT_V(n) asm volatile("s_waitcnt vmcnt(" #n ")" ::: "memory")
; #define PG8_WAIT_L(n) asm volatile("s_waitcnt lgkmcnt(" #n ")" ::: "memory")
; #define PG8_BAR __builtin_amdgcn_s_barrier()
; #define PG8_SCHED __builtin_amdgcn_sched_barrier(0)
; template <class Epi, class Sched>
; __device__ __forceinline__ void gemm_phase(LAS unsigned char* lds, const Gemm g, const Sched& S, const Epi& E, const int wid) {
;     ...
;             PG8_LDB(B0, 1, 0); PG8_LDB(B1, 1, 1); PG8_SCHED; PG8_LDA(At, 1, 0); PG8_STAGE(PG8_SA(0, 1), a2 + hstep, voffA);
;             PG8_WAIT_V(8); PG8_WAIT_L(0); PG8_BAR; PG8_MMA(0, 0, At, B0); PG8_MMA(0, 1, At, B1); PG8_BAR; PG8_SCHED;
	s_add_i32 s80, 0, 0x18000
	v_add_u32_e32 v0, s80, v160
	s_add_i32 s81, 0, 0x1c000
	ds_read_b128 v[130:133], v0
	ds_read_b128 v[134:137], v0 offset:1024
	ds_read_b128 v[156:159], v0 offset:2048
	ds_read_b128 v[192:195], v0 offset:3072
	v_add_u32_e32 v0, s81, v160
	ds_read_b128 v[196:199], v0
	ds_read_b128 v[200:203], v0 offset:1024
	ds_read_b128 v[204:207], v0 offset:2048
	ds_read_b128 v[208:211], v0 offset:3072
	s_add_u32 s22, s22, 0x80000
	s_addc_u32 s23, s23, 0
	s_mov_b32 m0, s33
	v_lshl_add_u64 v[188:189], s[22:23], 0, v[138:139]
	ds_read_b128 v[212:215], v183 offset:32768
	ds_read_b128 v[216:219], v183 offset:33792
	ds_read_b128 v[220:223], v183 offset:34816
	ds_read_b128 v[224:227], v183 offset:35840
	ds_read_b128 v[228:231], v183 offset:36864
	ds_read_b128 v[232:235], v183 offset:37888
	ds_read_b128 v[236:239], v183 offset:38912
	ds_read_b128 v[240:243], v183 offset:39936
	global_load_lds_dwordx4 v[188:189], off
	v_lshl_add_u64 v[188:189], s[22:23], 0, v[142:143]
	s_mov_b32 m0, s26
	s_nop 0
	global_load_lds_dwordx4 v[188:189], off
	s_waitcnt vmcnt(8)
	s_waitcnt lgkmcnt(0)
	s_barrier
	s_setprio 1
	s_waitcnt lgkmcnt(0)
	v_mfma_f32_16x16x32_bf16 v[126:129], v[130:133], v[212:215], v[126:129]
	v_mfma_f32_16x16x32_bf16 v[122:125], v[156:159], v[212:215], v[122:125]
	v_mfma_f32_16x16x32_bf16 v[110:113], v[130:133], v[220:223], v[110:113]
	v_mfma_f32_16x16x32_bf16 v[106:109], v[156:159], v[220:223], v[106:109]
	v_mfma_f32_16x16x32_bf16 v[94:97], v[130:133], v[228:231], v[94:97]
	v_mfma_f32_16x16x32_bf16 v[90:93], v[156:159], v[228:231], v[90:93]
	v_mfma_f32_16x16x32_bf16 v[78:81], v[130:133], v[236:239], v[78:81]
	v_mfma_f32_16x16x32_bf16 v[74:77], v[156:159], v[236:239], v[74:77]
	v_mfma_f32_16x16x32_bf16 v[126:129], v[134:137], v[216:219], v[126:129]
	v_mfma_f32_16x16x32_bf16 v[122:125], v[192:195], v[216:219], v[122:125]
	v_mfma_f32_16x16x32_bf16 v[110:113], v[134:137], v[224:227], v[110:113]
	v_mfma_f32_16x16x32_bf16 v[106:109], v[192:195], v[224:227], v[106:109]
	v_mfma_f32_16x16x32_bf16 v[94:97], v[134:137], v[232:235], v[94:97]
	v_mfma_f32_16x16x32_bf16 v[90:93], v[192:195], v[232:235], v[90:93]
	v_mfma_f32_16x16x32_bf16 v[78:81], v[134:137], v[240:243], v[78:81]
	v_mfma_f32_16x16x32_bf16 v[74:77], v[192:195], v[240:243], v[74:77]
	s_setprio 0
	s_setprio 1
	v_mfma_f32_16x16x32_bf16 v[118:121], v[196:199], v[212:215], v[118:121]
	v_mfma_f32_16x16x32_bf16 v[114:117], v[204:207], v[212:215], v[114:117]
	v_mfma_f32_16x16x32_bf16 v[102:105], v[196:199], v[220:223], v[102:105]
	v_mfma_f32_16x16x32_bf16 v[98:101], v[204:207], v[220:223], v[98:101]
	v_mfma_f32_16x16x32_bf16 v[86:89], v[196:199], v[228:231], v[86:89]
	v_mfma_f32_16x16x32_bf16 v[82:85], v[204:207], v[228:231], v[82:85]
	v_mfma_f32_16x16x32_bf16 v[70:73], v[196:199], v[236:239], v[70:73]
	v_mfma_f32_16x16x32_bf16 v[66:69], v[204:207], v[236:239], v[66:69]
	v_mfma_f32_16x16x32_bf16 v[118:121], v[200:203], v[216:219], v[118:121]
	v_mfma_f32_16x16x32_bf16 v[114:117], v[208:211], v[216:219], v[114:117]
	v_mfma_f32_16x16x32_bf16 v[102:105], v[200:203], v[224:227], v[102:105]
	v_mfma_f32_16x16x32_bf16 v[98:101], v[208:211], v[224:227], v[98:101]
	v_mfma_f32_16x16x32_bf16 v[86:89], v[200:203], v[232:235], v[86:89]
	v_mfma_f32_16x16x32_bf16 v[82:85], v[208:211], v[232:235], v[82:85]
	v_mfma_f32_16x16x32_bf16 v[70:73], v[200:203], v[240:243], v[70:73]
	v_mfma_f32_16x16x32_bf16 v[66:69], v[208:211], v[240:243], v[66:69]
	s_setprio 0
	s_barrier
; #define PG8_STAGE(bufoff, gbase, voff) do { _Pragma("unroll") for (int _i = 0; _i < 2; ++_i) \
;         __builtin_amdgcn_global_load_lds((const unsigned*)((const char*)(gbase) + (voff)[_i]), (LAS unsigned*)(lds + (bufoff) + ldsw + _i * 8192), 16, 0, 0); } while (0)
; #define PG8_LDA(dst, b, h) do { _Pragma("unroll") for (int m = 0; m < 4; ++m) _Pragma("unroll") for (int k = 0; k < 2; ++k) dst[m][k] = *(const LAS bf16x8*)(lds + PG8_SA(b, h) + aoff + m * 2048 + k * 1024); } while (0)
; #define PG8_MMA(ai, bj, At, Bt) do { __builtin_amdgcn_s_setprio(1); _Pragma("unroll") for (int m = 0; m < 4; ++m) _Pragma("unroll") for (int n = 0; n < 2; ++n) _Pragma("unroll") for (int k = 0; k < 2; ++k) \
;         acc[ai][bj][m][n] = __builtin_amdgcn_mfma_f32_16x16x32_bf16(Bt[n][k], At[m][k], acc[ai][bj][m][n], 0, 0, 0); __builtin_amdgcn_s_setprio(0); } while (0)
; #define PG8_WAIT_V(n) asm volatile("s_waitcnt vmcnt(" #n ")" ::: "memory")
; #define PG8_WAIT_L(n) asm volatile("s_waitcnt lgkmcnt(" #n ")" ::: "memory")
; #define PG8_BAR __builtin_amdgcn_s_barrier()
; #define PG8_SCHED __builtin_amdgcn_sched_barrier(0)
; template <class Epi, class Sched>
; __device__ __forceinline__ void gemm_phase(LAS unsigned char* lds, const Gemm g, const Sched& S, const Epi& E, const int wid) {
;     ...
;         for (int t = 0; t < nt; t += 2) {
;     ...
;             PG8_LDA(At, 1, 1); PG8_STAGE(PG8_SB(1, 0), b3, voffB); PG8_STAGE(PG8_SB(1, 1), b3 + bstep, voffB); PG8_STAGE(PG8_SA(1, 0), a3, voffA);
;             PG8_WAIT_V(8); PG8_WAIT_L(0); PG8_BAR; PG8_MMA(1, 0, At, B0); PG8_MMA(1, 1, At, B1); PG8_BAR; PG8_SCHED;
	s_add_i32 s22, s80, s97
	v_lshl_add_u64 v[188:189], v[244:245], 0, s[86:87]
	s_mov_b32 m0, s22
	ds_read_b128 v[212:215], v183 offset:49152
	ds_read_b128 v[216:219], v183 offset:50176
	ds_read_b128 v[220:223], v183 offset:51200
	ds_read_b128 v[224:227], v183 offset:52224
	ds_read_b128 v[228:231], v183 offset:53248
	ds_read_b128 v[232:235], v183 offset:54272
	ds_read_b128 v[236:239], v183 offset:55296
	ds_read_b128 v[240:243], v183 offset:56320
	global_load_lds_dwordx4 v[188:189], off
	s_add_i32 m0, s22, 0x2000
	s_add_u32 s20, s20, 0x20080
	v_lshl_add_u64 v[188:189], v[246:247], 0, s[86:87]
	s_addc_u32 s21, s21, 0
	s_add_i32 s22, s81, s97
	global_load_lds_dwordx4 v[188:189], off
	v_lshl_add_u64 v[188:189], s[20:21], 0, v[140:141]
	s_mov_b32 m0, s22
	v_lshl_add_u64 v[162:163], v[162:163], 0, s[86:87]
	global_load_lds_dwordx4 v[188:189], off
	v_lshl_add_u64 v[188:189], s[20:21], 0, v[144:145]
	s_add_i32 m0, s22, 0x2000
	s_nop 0
	global_load_lds_dwordx4 v[188:189], off
	v_lshl_add_u64 v[188:189], v[248:249], 0, s[86:87]
	s_mov_b32 m0, s35
	s_nop 0
	global_load_lds_dwordx4 v[188:189], off
	s_mov_b32 m0, s84
	s_nop 0
	global_load_lds_dwordx4 v[162:163], off
	s_waitcnt vmcnt(8)
	s_waitcnt lgkmcnt(0)
	s_barrier
	s_setprio 1
	s_waitcnt lgkmcnt(0)
	v_mfma_f32_16x16x32_bf16 v[62:65], v[130:133], v[212:215], v[62:65]
	v_mfma_f32_16x16x32_bf16 v[58:61], v[156:159], v[212:215], v[58:61]
	v_mfma_f32_16x16x32_bf16 v[46:49], v[130:133], v[220:223], v[46:49]
	v_mfma_f32_16x16x32_bf16 v[42:45], v[156:159], v[220:223], v[42:45]
	v_mfma_f32_16x16x32_bf16 v[30:33], v[130:133], v[228:231], v[30:33]
	v_mfma_f32_16x16x32_bf16 v[26:29], v[156:159], v[228:231], v[26:29]
	v_mfma_f32_16x16x32_bf16 v[14:17], v[130:133], v[236:239], v[14:17]
	v_mfma_f32_16x16x32_bf16 v[10:13], v[156:159], v[236:239], v[10:13]
	v_mfma_f32_16x16x32_bf16 v[62:65], v[134:137], v[216:219], v[62:65]
	v_mfma_f32_16x16x32_bf16 v[58:61], v[192:195], v[216:219], v[58:61]
	v_mfma_f32_16x16x32_bf16 v[46:49], v[134:137], v[224:227], v[46:49]
	v_mfma_f32_16x16x32_bf16 v[42:45], v[192:195], v[224:227], v[42:45]
	v_mfma_f32_16x16x32_bf16 v[30:33], v[134:137], v[232:235], v[30:33]
	v_mfma_f32_16x16x32_bf16 v[26:29], v[192:195], v[232:235], v[26:29]
	v_mfma_f32_16x16x32_bf16 v[14:17], v[134:137], v[240:243], v[14:17]
	v_mfma_f32_16x16x32_bf16 v[10:13], v[192:195], v[240:243], v[10:13]
	s_setprio 0
	s_setprio 1
	v_mfma_f32_16x16x32_bf16 v[54:57], v[196:199], v[212:215], v[54:57]
	v_mfma_f32_16x16x32_bf16 v[50:53], v[204:207], v[212:215], v[50:53]
	v_mfma_f32_16x16x32_bf16 v[38:41], v[196:199], v[220:223], v[38:41]
	v_mfma_f32_16x16x32_bf16 v[34:37], v[204:207], v[220:223], v[34:37]
	v_mfma_f32_16x16x32_bf16 v[22:25], v[196:199], v[228:231], v[22:25]
	v_mfma_f32_16x16x32_bf16 v[18:21], v[204:207], v[228:231], v[18:21]
	v_mfma_f32_16x16x32_bf16 v[6:9], v[196:199], v[236:239], v[6:9]
	v_mfma_f32_16x16x32_bf16 v[2:5], v[204:207], v[236:239], v[2:5]
	v_mfma_f32_16x16x32_bf16 v[54:57], v[200:203], v[216:219], v[54:57]
	v_mfma_f32_16x16x32_bf16 v[50:53], v[208:211], v[216:219], v[50:53]
	v_mfma_f32_16x16x32_bf16 v[38:41], v[200:203], v[224:227], v[38:41]
	v_mfma_f32_16x16x32_bf16 v[34:37], v[208:211], v[224:227], v[34:37]
	v_mfma_f32_16x16x32_bf16 v[22:25], v[200:203], v[232:235], v[22:25]
	v_mfma_f32_16x16x32_bf16 v[18:21], v[208:211], v[232:235], v[18:21]
	v_mfma_f32_16x16x32_bf16 v[6:9], v[200:203], v[240:243], v[6:9]
	v_mfma_f32_16x16x32_bf16 v[2:5], v[208:211], v[240:243], v[2:5]
	s_setprio 0
	s_barrier
	s_add_i32 s79, s79, 2
	s_add_u32 s18, s18, 0x100
	s_addc_u32 s19, s19, 0
	s_add_u32 s44, s44, 0x100
	s_addc_u32 s78, s78, 0
	s_cmp_gt_u32 s79, 29
